# phase F sample-row split-K GEMM: 2-D task mapping (4 weight n-tiles x 2 m-tiles per block), 24 fragment loads per wave instead of 36, all in flight
# speedup vs baseline: 1.0187x; 1.0063x over previous
; __device__ __forceinline__ int lane_fresh() { int l; asm volatile("v_mbcnt_lo_u32_b32 %0, -1, 0\n\tv_mbcnt_hi_u32_b32 %0, -1, %0" : "=v"(l)); return l; }
; #define MFMA16(a, b, c) __builtin_amdgcn_mfma_f32_16x16x32_bf16((a), (b), (c), 0, 0, 0)
; template <int NT, class FA, class FB, class FL>
; __device__ __forceinline__ void skgemm(FA aptr, FB bptr, FL ldf, const int KS, const int wv) {
;   float* part = (float*)g_shm;
;   const int lane = lane_fresh(), fr = lane & 15, fq = lane >> 4;
;   __syncthreads();
; #pragma unroll
;   for (int i = 0; i < NT; ++i) {
;     f32x4 acc = {0.f, 0.f, 0.f, 0.f};
;     const int ld = ldf(i);
;     const u16* ap = aptr(i) + (size_t)fr * ld + wv * KS + fq * 8;
;     const u16* bp = bptr(i) + (size_t)fr * ld + wv * KS + fq * 8;
; #pragma unroll 8
;     for (int k = 0; k < KS; k += 32) acc = MFMA16(*(const bf16x8*)(bp + k), *(const bf16x8*)(ap + k), acc);
;     *(f32x4*)(part + ((i * 8 + wv) * 64 + lane) * 4) = acc;
;   }
;   __syncthreads();
; __device__ __forceinline__ void phaseF(const Params& p, const int wv, const int rep) {
;     ...
;   for (int gb = blockIdx.x; gb < 256; gb += gridDim.x) {
;     const int task0 = gb * 8, mt = task0 >> 8, nt0 = task0 & 255;
;     const u16* Ab = H2B + (size_t)(TP + mt * 16) * 1024;
;     skgemm<8>([&](int) { return Ab; }, [&](int i) { return WUP + (size_t)((nt0 + i) * 16) * 1024; }, [&](int) { return 1024; }, 128, wv);
.LBB0_1077:
	s_and_b32 s98, s43, 63
	s_lshl_b32 s98, s98, 2
	s_lshr_b32 s99, s43, 6
	s_lshl_b32 s99, s99, 5
	s_addk_i32 s99, 0x4000
	v_mbcnt_lo_u32_b32 v3, -1, 0
	v_mbcnt_hi_u32_b32 v3, -1, v3
	s_lshl_b32 s28, s99, 11
	s_add_u32 s52, s8, s28
	s_addc_u32 s53, s9, 0
	s_lshl_b32 s28, s98, 15
	s_add_u32 s28, s33, s28
	s_addc_u32 s29, s44, 0
	v_and_b32_e32 v200, 15, v3
	v_lshlrev_b32_e32 v200, 11, v200
	v_lshrrev_b32_e32 v201, 4, v3
	v_lshl_add_u32 v200, v201, 4, v200
	v_add_u32_e32 v200, s4, v200
	v_lshl_add_u32 v201, v3, 4, s30
	s_barrier
	global_load_dwordx4 v[64:67], v200, s[52:53]
	global_load_dwordx4 v[68:71], v200, s[52:53] offset:64
	global_load_dwordx4 v[72:75], v200, s[52:53] offset:128
	global_load_dwordx4 v[76:79], v200, s[52:53] offset:192
	global_load_dwordx4 v[96:99], v200, s[28:29]
	global_load_dwordx4 v[100:103], v200, s[28:29] offset:64
	global_load_dwordx4 v[104:107], v200, s[28:29] offset:128
	global_load_dwordx4 v[108:111], v200, s[28:29] offset:192
	s_add_u32 s28, s28, 0x8000
	s_addc_u32 s29, s29, 0
	global_load_dwordx4 v[112:115], v200, s[28:29]
	global_load_dwordx4 v[116:119], v200, s[28:29] offset:64
	global_load_dwordx4 v[120:123], v200, s[28:29] offset:128
	global_load_dwordx4 v[124:127], v200, s[28:29] offset:192
	s_add_u32 s28, s28, 0x8000
	s_addc_u32 s29, s29, 0
	global_load_dwordx4 v[128:131], v200, s[28:29]
	global_load_dwordx4 v[132:135], v200, s[28:29] offset:64
	global_load_dwordx4 v[136:139], v200, s[28:29] offset:128
	global_load_dwordx4 v[140:143], v200, s[28:29] offset:192
	s_add_u32 s28, s28, 0x8000
	s_addc_u32 s29, s29, 0
	global_load_dwordx4 v[144:147], v200, s[28:29]
	global_load_dwordx4 v[148:151], v200, s[28:29] offset:64
	global_load_dwordx4 v[152:155], v200, s[28:29] offset:128
	global_load_dwordx4 v[156:159], v200, s[28:29] offset:192
	s_add_u32 s28, s28, 0x8000
	s_addc_u32 s29, s29, 0
	s_add_u32 s52, s52, 0x8000
	s_addc_u32 s53, s53, 0
	global_load_dwordx4 v[80:83], v200, s[52:53]
	global_load_dwordx4 v[84:87], v200, s[52:53] offset:64
	global_load_dwordx4 v[88:91], v200, s[52:53] offset:128
	global_load_dwordx4 v[92:95], v200, s[52:53] offset:192
	s_add_i32 s43, s43, s54
	s_add_i32 s55, s55, s56
	s_waitcnt vmcnt(19)
	v_mfma_f32_16x16x32_bf16 v[160:163], v[96:99], v[64:67], 0
	s_waitcnt vmcnt(18)
	v_mfma_f32_16x16x32_bf16 v[160:163], v[100:103], v[68:71], v[160:163]
	s_waitcnt vmcnt(17)
	v_mfma_f32_16x16x32_bf16 v[160:163], v[104:107], v[72:75], v[160:163]
	s_waitcnt vmcnt(16)
	v_mfma_f32_16x16x32_bf16 v[160:163], v[108:111], v[76:79], v[160:163]
	s_waitcnt vmcnt(15)
	v_mfma_f32_16x16x32_bf16 v[164:167], v[112:115], v[64:67], 0
	s_waitcnt vmcnt(14)
	v_mfma_f32_16x16x32_bf16 v[164:167], v[116:119], v[68:71], v[164:167]
	s_waitcnt vmcnt(13)
	v_mfma_f32_16x16x32_bf16 v[164:167], v[120:123], v[72:75], v[164:167]
	s_waitcnt vmcnt(12)
	v_mfma_f32_16x16x32_bf16 v[164:167], v[124:127], v[76:79], v[164:167]
	s_waitcnt vmcnt(11)
	v_mfma_f32_16x16x32_bf16 v[168:171], v[128:131], v[64:67], 0
	s_waitcnt vmcnt(10)
	v_mfma_f32_16x16x32_bf16 v[168:171], v[132:135], v[68:71], v[168:171]
	s_waitcnt vmcnt(9)
	v_mfma_f32_16x16x32_bf16 v[168:171], v[136:139], v[72:75], v[168:171]
	s_waitcnt vmcnt(8)
	v_mfma_f32_16x16x32_bf16 v[168:171], v[140:143], v[76:79], v[168:171]
	ds_write_b128 v201, v[160:163]
	s_waitcnt vmcnt(7)
	v_mfma_f32_16x16x32_bf16 v[172:175], v[144:147], v[64:67], 0
	s_waitcnt vmcnt(6)
	v_mfma_f32_16x16x32_bf16 v[172:175], v[148:151], v[68:71], v[172:175]
	s_waitcnt vmcnt(5)
	v_mfma_f32_16x16x32_bf16 v[172:175], v[152:155], v[72:75], v[172:175]
	s_waitcnt vmcnt(4)
	v_mfma_f32_16x16x32_bf16 v[172:175], v[156:159], v[76:79], v[172:175]
	ds_write_b128 v201, v[164:167] offset:8192
	s_waitcnt vmcnt(3)
	v_mfma_f32_16x16x32_bf16 v[176:179], v[96:99], v[80:83], 0
	s_waitcnt vmcnt(2)
	v_mfma_f32_16x16x32_bf16 v[176:179], v[100:103], v[84:87], v[176:179]
	s_waitcnt vmcnt(1)
	v_mfma_f32_16x16x32_bf16 v[176:179], v[104:107], v[88:91], v[176:179]
	s_waitcnt vmcnt(0)
	v_mfma_f32_16x16x32_bf16 v[176:179], v[108:111], v[92:95], v[176:179]
	ds_write_b128 v201, v[168:171] offset:16384
	s_waitcnt vmcnt(3)
	v_mfma_f32_16x16x32_bf16 v[180:183], v[112:115], v[80:83], 0
	s_waitcnt vmcnt(2)
	v_mfma_f32_16x16x32_bf16 v[180:183], v[116:119], v[84:87], v[180:183]
	s_waitcnt vmcnt(1)
	v_mfma_f32_16x16x32_bf16 v[180:183], v[120:123], v[88:91], v[180:183]
	s_waitcnt vmcnt(0)
	v_mfma_f32_16x16x32_bf16 v[180:183], v[124:127], v[92:95], v[180:183]
	ds_write_b128 v201, v[172:175] offset:24576
	s_waitcnt vmcnt(3)
	v_mfma_f32_16x16x32_bf16 v[184:187], v[128:131], v[80:83], 0
	s_waitcnt vmcnt(2)
	v_mfma_f32_16x16x32_bf16 v[184:187], v[132:135], v[84:87], v[184:187]
	s_waitcnt vmcnt(1)
	v_mfma_f32_16x16x32_bf16 v[184:187], v[136:139], v[88:91], v[184:187]
	s_waitcnt vmcnt(0)
	v_mfma_f32_16x16x32_bf16 v[184:187], v[140:143], v[92:95], v[184:187]
	ds_write_b128 v201, v[176:179] offset:32768
	s_waitcnt vmcnt(3)
	v_mfma_f32_16x16x32_bf16 v[188:191], v[144:147], v[80:83], 0
	s_waitcnt vmcnt(2)
	v_mfma_f32_16x16x32_bf16 v[188:191], v[148:151], v[84:87], v[188:191]
	s_waitcnt vmcnt(1)
	v_mfma_f32_16x16x32_bf16 v[188:191], v[152:155], v[88:91], v[188:191]
	s_waitcnt vmcnt(0)
	v_mfma_f32_16x16x32_bf16 v[188:191], v[156:159], v[92:95], v[188:191]
	ds_write_b128 v201, v[180:183] offset:40960
	s_nop 7
	ds_write_b128 v201, v[184:187] offset:49152
	ds_write_b128 v201, v[188:191] offset:57344
	s_waitcnt lgkmcnt(0)
	s_barrier
; __device__ __forceinline__ u32x2 pack4(f32x4 v) { u32x2 r; r.x = cvt_pk(v[0], v[1]); r.y = cvt_pk(v[2], v[3]); return r; }
; __device__ __forceinline__ int lane_fresh() { int l; asm volatile("v_mbcnt_lo_u32_b32 %0, -1, 0\n\tv_mbcnt_hi_u32_b32 %0, -1, %0" : "=v"(l)); return l; }
; __device__ __forceinline__ float shfl_xor_f(float v, int mask) { const int l = lane_fresh(); return __int_as_float(__builtin_amdgcn_ds_bpermute((l ^ mask) << 2, __float_as_int(v))); }
; __device__ __forceinline__ void phaseF(const Params& p, const int wv, const int rep) {
;     ...
;     {
;       const int lane_e = lane_fresh(), fr = lane_e & 15, fq = lane_e >> 4;
;       const int ntl = nt0 + wv, row = TP + mt * 16 + fr, col = ntl * 16 + fq * 4;
;       const float* ps = PSS + (size_t)(row - TP) * 64 + fq * 16;
;       f32x4 a4 = *(const f32x4*)ps + *(const f32x4*)(ps + 4) + *(const f32x4*)(ps + 8) + *(const f32x4*)(ps + 12);
;       float sq = a4[0] + a4[1] + a4[2] + a4[3];
;       sq += shfl_xor_f(sq, 16); sq += shfl_xor_f(sq, 32);
;       const float rstd = rsqrtf(sq * (1.f / 1024.f) + EPS);
;       f32x4 v = skreduce(wv) * rstd;
; #pragma unroll
;       for (int e = 0; e < 4; ++e) { float r = fmaxf(v[e], 0.f); v[e] = r * r; }
;       *(u32x2*)(ACT + (size_t)row * 4096 + col) = pack4(v);
;     }
	s_lshr_b32 s28, s90, 2
	s_lshl_b32 s28, s28, 4
	s_add_i32 s28, s28, s99
	s_and_b32 s45, s90, 3
	s_add_i32 s45, s45, s98
	v_mbcnt_lo_u32_b32 v0, -1, 0
	v_mbcnt_hi_u32_b32 v0, -1, v0
	s_nop 0
	v_and_or_b32 v20, v0, 15, s28
	v_ashrrev_i32_e32 v21, 31, v20
	v_and_b32_e32 v4, -16, v0
	v_lshlrev_b64 v[6:7], 8, v[20:21]
	v_ashrrev_i32_e32 v5, 31, v4
	v_lshl_add_u64 v[6:7], s[10:11], 0, v[6:7]
	v_lshl_add_u64 v[4:5], v[4:5], 2, v[6:7]
	v_lshl_add_u64 v[16:17], v[4:5], 0, s[26:27]
	v_add_co_u32_e32 v4, vcc, s41, v4
	v_ashrrev_i32_e32 v0, 2, v0
	s_nop 0
	v_addc_co_u32_e32 v5, vcc, -1, v5, vcc
	global_load_dwordx4 v[4:7], v[4:5], off
	s_nop 0
	global_load_dwordx4 v[8:11], v[16:17], off offset:16
	global_load_dwordx4 v[12:15], v[16:17], off offset:32
	s_nop 0
	global_load_dwordx4 v[16:19], v[16:17], off offset:48
	v_and_b32_e32 v0, -4, v0
	v_lshl_add_u32 v22, s45, 4, v0
	v_mbcnt_lo_u32_b32 v0, -1, 0
	v_mbcnt_hi_u32_b32 v0, -1, v0
	v_mbcnt_lo_u32_b32 v3, -1, 0
	v_mbcnt_hi_u32_b32 v3, -1, v3
	v_lshlrev_b64 v[20:21], 13, v[20:21]
	v_lshlrev_b32_e32 v0, 2, v0
	v_xor_b32_e32 v0, 64, v0
	v_lshlrev_b32_e32 v3, 2, v3
	v_xor_b32_e32 v3, 0x80, v3
	v_lshl_add_u64 v[20:21], s[2:3], 0, v[20:21]
	v_ashrrev_i32_e32 v23, 31, v22
	v_lshl_add_u64 v[52:53], v[22:23], 1, v[20:21]
	v_mbcnt_lo_u32_b32 v20, -1, 0
	v_mbcnt_hi_u32_b32 v20, -1, v20
	s_waitcnt vmcnt(2)
	v_pk_add_f32 v[4:5], v[4:5], v[8:9]
	v_pk_add_f32 v[6:7], v[6:7], v[10:11]
	s_waitcnt vmcnt(1)
	v_pk_add_f32 v[4:5], v[4:5], v[12:13]
	v_pk_add_f32 v[6:7], v[6:7], v[14:15]
	s_waitcnt vmcnt(0)
	v_pk_add_f32 v[4:5], v[4:5], v[16:17]
	v_pk_add_f32 v[6:7], v[6:7], v[18:19]
	v_add_f32_e32 v4, v4, v5
	v_add_f32_e32 v4, v6, v4
	v_add_f32_e32 v4, v7, v4
	ds_bpermute_b32 v0, v0, v4
	v_lshl_add_u32 v48, v20, 4, s31
	ds_read_b128 v[20:23], v48
	ds_read_b128 v[24:27], v48 offset:1024
	ds_read_b128 v[28:31], v48 offset:2048
	ds_read_b128 v[32:35], v48 offset:3072
	ds_read_b128 v[36:39], v48 offset:4096
	ds_read_b128 v[40:43], v48 offset:5120
	ds_read_b128 v[44:47], v48 offset:6144
	ds_read_b128 v[48:51], v48 offset:7168
	s_waitcnt lgkmcnt(7)
	v_pk_add_f32 v[22:23], v[22:23], 0 op_sel_hi:[1,0]
	v_pk_add_f32 v[20:21], v[20:21], 0 op_sel_hi:[1,0]
	v_add_f32_e32 v0, v4, v0
	ds_bpermute_b32 v3, v3, v0
	s_waitcnt lgkmcnt(7)
	v_pk_add_f32 v[22:23], v[22:23], v[26:27]
	v_pk_add_f32 v[20:21], v[20:21], v[24:25]
	s_waitcnt lgkmcnt(6)
	v_pk_add_f32 v[22:23], v[22:23], v[30:31]
	v_pk_add_f32 v[20:21], v[20:21], v[28:29]
	s_waitcnt lgkmcnt(0)
	v_add_f32_e32 v0, v0, v3
	v_fmamk_f32 v0, v0, 0x3a800000, v2
	v_mul_f32_e32 v3, 0x4b800000, v0
	v_cmp_gt_f32_e32 vcc, s42, v0
	v_pk_add_f32 v[22:23], v[22:23], v[34:35]
	v_pk_add_f32 v[20:21], v[20:21], v[32:33]
	v_cndmask_b32_e32 v0, v0, v3, vcc
	v_rsq_f32_e32 v0, v0
	v_pk_add_f32 v[22:23], v[22:23], v[38:39]
	v_pk_add_f32 v[20:21], v[20:21], v[36:37]
	v_pk_add_f32 v[22:23], v[22:23], v[42:43]
	v_pk_add_f32 v[20:21], v[20:21], v[40:41]
	v_pk_add_f32 v[22:23], v[22:23], v[46:47]
	v_pk_add_f32 v[20:21], v[20:21], v[44:45]
	v_mul_f32_e32 v3, 0x45800000, v0
	v_pk_add_f32 v[22:23], v[22:23], v[50:51]
	v_pk_add_f32 v[20:21], v[20:21], v[48:49]
	v_cndmask_b32_e32 v0, v0, v3, vcc
	v_pk_mul_f32 v[4:5], v[22:23], v[0:1] op_sel_hi:[1,0]
	v_pk_mul_f32 v[6:7], v[20:21], v[0:1] op_sel_hi:[1,0]
	v_max_f32_e32 v4, 0, v4
	v_max_f32_e32 v6, 0, v6
	v_max_f32_e32 v7, 0, v7
	v_max_f32_e32 v5, 0, v5
	v_pk_mul_f32 v[6:7], v[6:7], v[6:7]
	v_pk_mul_f32 v[4:5], v[4:5], v[4:5]
	v_cvt_pk_bf16_f32 v6, v6, v7
	v_cvt_pk_bf16_f32 v7, v4, v5
	global_store_dwordx2 v[52:53], v[6:7], off
	s_cmpk_lt_i32 s43, 0x100
	s_cbranch_scc1 .LBB0_1077
